# v52 with the preparation on 112 workgroups
# speedup vs baseline: 1.0583x; 1.0063x over previous
; __device__ __forceinline__ void p2_rwkv_prep(const Params& P, float* lds) {
;     ...
;     } else {
; #pragma unroll
;         for (int mt = 0; mt < 2; ++mt)
; #pragma unroll
;             for (int nt = 0; nt < 4; ++nt)
; #pragma unroll
;                 for (int s = 0; s < 2; ++s)
; #pragma unroll
;                     for (int j = 0; j < 8; ++j) { wbh[mt][nt][s][j] = 0; wbl[mt][nt][s][j] = 0; }
;         mux = P.mu_shift[1152 + (tid - RW)];
; __global__ void __launch_bounds__(512, 2) mk_fwd(Params P) {
;     ...
;     if (IN(2)) {
;         if (blockIdx.x < NPREP) {
;             p2_rwkv_prep(P, ldsf);
.LBB0_699:
	s_cmp_lt_i32 s60, 3
	s_cselect_b64 s[2:3], -1, 0
	s_and_b64 s[0:1], s[2:3], s[0:1]
	s_andn2_b64 vcc, exec, s[0:1]
	s_cbranch_vccnz .LBB0_939
	s_cmpk_gt_u32 s56, 0x6f
	s_cbranch_scc1 .LBB0_905
	s_movk_i32 s0, 0x180
	v_cmp_gt_u32_e64 s[4:5], s0, v0
	s_movk_i32 s0, 0x17f
	v_cmp_lt_u32_e32 vcc, s0, v0
	s_and_saveexec_b64 s[0:1], vcc
	s_xor_b64 s[0:1], exec, s[0:1]
	s_cbranch_execz .LBB0_703
	v_readlane_b32 s8, v252, 16
	v_lshlrev_b32_e32 v1, 2, v0
	v_readlane_b32 s18, v252, 26
	v_readlane_b32 s19, v252, 27
	v_readlane_b32 s9, v252, 17
	v_readlane_b32 s10, v252, 18
	v_readlane_b32 s11, v252, 19
	v_readlane_b32 s12, v252, 20
	v_readlane_b32 s13, v252, 21
	global_load_dword v173, v1, s[18:19] offset:3072
	v_readlane_b32 s14, v252, 22
	v_readlane_b32 s15, v252, 23
	v_readlane_b32 s16, v252, 24
	v_readlane_b32 s17, v252, 25
	v_readlane_b32 s20, v252, 28
	v_readlane_b32 s21, v252, 29
	v_readlane_b32 s22, v252, 30
	v_readlane_b32 s23, v252, 31

; __device__ __forceinline__ float bf2f(bf16_t b) { return __uint_as_float(((unsigned)b) << 16); }
; __device__ __forceinline__ void p2_rwkv_prep(const Params& P, float* lds) {
;     ...
;     int ch = blockIdx.x;
;     if (tid >= RW && ch < NCHK) prep_produce(P, prw, ch, xbuf, tid - RW, mux);
;     for (int it = 0; ch < NCHK; ch += NPREP, ++it) {
;         const int tok0 = ch * CT;
;         float* bufc = xbuf + (it & 1) * (CT * 128); float* bufn = xbuf + ((it + 1) & 1) * (CT * 128);
;         float nr[4], nk[4], nv[4], qr = 0.f, qk = 0.f, qv = 0.f;
;         if (tid < RW) {
; #pragma unroll
;             for (int q = 0; q < 4; ++q) { const bf16_t* p = prw + (size_t)(tok0 + q) * RCOLS + tid; nr[q] = bf2f(p[0]); nk[q] = bf2f(p[RW]); nv[q] = bf2f(p[2 * RW]); }
.LBB0_760:
	s_or_b64 exec, exec, s[2:3]
	v_lshl_add_u32 v130, v170, 12, 0
	v_lshlrev_b32_e32 v132, 1, v0
	v_mov_b32_e32 v133, 0
	v_lshlrev_b32_e32 v134, 9, v0
	v_lshlrev_b32_e32 v172, 2, v1
	v_lshlrev_b32_e32 v131, 10, v170
	v_lshl_add_u64 v[176:177], s[0:1], 0, v[132:133]
	v_and_b32_e32 v134, 0xe00, v134
	v_and_b32_e32 v132, 0x60, v132
	v_add_u32_e32 v199, v130, v172
	s_load_dwordx16 s[36:51], s[58:59], 0x0
	v_add3_u32 v198, 0, v134, v132
	v_and_b32_e32 v132, 8, v0
	v_sub_u32_e32 v200, v199, v131
	v_cmp_eq_u32_e64 s[8:9], 0, v132
	v_and_b32_e32 v132, 15, v0
	v_mad_u32_u24 v131, v1, 12, v200
	s_add_u32 s18, s78, 0xa2d4000
	v_lshl_add_u32 v134, v132, 2, v130
	v_lshlrev_b32_e32 v130, 6, v0
	v_mad_i32_i24 v203, v1, -12, v131
	s_addc_u32 s19, s79, 0
	v_cmp_gt_u32_e64 s[10:11], 32, v1
	v_cmp_eq_u32_e64 s[12:13], 0, v1
	v_and_b32_e32 v130, 0x400, v130
	v_mad_u32_u24 v1, v1, 12, v203
	v_lshlrev_b32_e32 v132, 2, v0
	v_lshl_add_u64 v[180:181], v[174:175], 1, s[0:1]
	s_lshl_b32 s0, s56, 3
	v_mov_b32_e32 v171, v133
	v_cmp_gt_u32_e64 s[14:15], 64, v174
	s_movk_i32 s22, 0x400
	v_add_u32_e32 v201, 0xa000, v131
	v_add_u32_e32 v202, 0xa400, v131
	v_add_u32_e32 v204, 0xa600, v1
	v_add_u32_e32 v205, 0xaa00, v1
	v_lshl_add_u32 v206, v174, 2, 0
	s_waitcnt lgkmcnt(0)
	v_lshl_add_u64 v[178:179], s[50:51], 0, v[132:133]
	s_add_i32 s23, s0, 0x387
	s_mov_b32 s24, 0x3fb8aa3b
	s_movk_i32 s25, 0x610
	s_mov_b32 s26, 0x3f200000
	s_mov_b32 s27, 0xc2ce8ed0
	s_mov_b32 s28, 0x42b17218
	v_mov_b32_e32 v207, 0x3ca908c9
	s_brev_b32 s29, -2
	v_mov_b32_e32 v208, 0xa00
	v_add_u32_e32 v209, v134, v130
	v_mov_b32_e32 v210, 0x1400
	v_mov_b32_e32 v211, 0x610
	v_mov_b32_e32 v212, 0x7f800000
	s_mov_b32 s30, s56
	s_branch .LBB0_764

; __device__ __forceinline__ float bf2f(bf16_t b) { return __uint_as_float(((unsigned)b) << 16); }
; __device__ __forceinline__ void p2_rwkv_prep(const Params& P, float* lds) {
;     ...
;     for (int it = 0; ch < NCHK; ch += NPREP, ++it) {
;         const int tok0 = ch * CT;
;         float* bufc = xbuf + (it & 1) * (CT * 128); float* bufn = xbuf + ((it + 1) & 1) * (CT * 128);
;         float nr[4], nk[4], nv[4], qr = 0.f, qk = 0.f, qv = 0.f;
;         if (tid < RW) {
; #pragma unroll
;             for (int q = 0; q < 4; ++q) { const bf16_t* p = prw + (size_t)(tok0 + q) * RCOLS + tid; nr[q] = bf2f(p[0]); nk[q] = bf2f(p[RW]); nv[q] = bf2f(p[2 * RW]); }
;             if (tok0 < NTOK && (tok0 & (SEQ - 1))) { const bf16_t* p = prw + (size_t)(tok0 - 1) * RCOLS + tid; qr = bf2f(p[0]); qk = bf2f(p[RW]); qv = bf2f(p[2 * RW]); }
.LBB0_763:
	s_or_b64 exec, exec, s[0:1]
	s_add_i32 s0, s30, 0x70
	s_addk_i32 s23, 0x380
	s_addk_i32 s22, 0x400
	s_cmpk_lt_i32 s30, 0x794
	s_mov_b32 s30, s0
	s_cbranch_scc0 .LBB0_901
.LBB0_764:
	s_cmpk_gt_i32 s30, 0x7ff
	s_cselect_b64 s[98:99], -1, 0
	v_mov_b32_e32 v255, 1.0
	s_add_i32 s31, s23, 0xfffffc79
	v_mov_b32_e32 v131, 0
	v_mov_b32_e32 v130, 0
	v_mov_b32_e32 v1, 0
	s_and_saveexec_b64 s[0:1], s[4:5]
	s_cbranch_execz .LBB0_768
	v_mad_u64_u32 v[130:131], s[2:3], s31, v208, v[176:177]
	s_add_i32 s2, s23, 0xfffffc7a
	s_nop 0
	v_mad_u64_u32 v[134:135], s[2:3], s2, v208, v[176:177]
	s_add_i32 s2, s23, 0xfffffc7b
	s_nop 0
	v_mad_u64_u32 v[146:147], s[2:3], s2, v208, v[176:177]
	global_load_ushort v141, v[130:131], off
	global_load_ushort v144, v[130:131], off offset:768
	global_load_ushort v139, v[134:135], off
	global_load_ushort v142, v[134:135], off offset:768
	s_nop 0
	global_load_ushort v135, v[134:135], off offset:1536
	s_nop 0
	global_load_ushort v134, v[146:147], off
	global_load_ushort v138, v[146:147], off offset:768
	global_load_ushort v143, v[130:131], off offset:1536
	s_add_i32 s2, s23, 0xfffffc7c
	v_mad_u64_u32 v[130:131], s[2:3], s2, v208, v[176:177]
	global_load_ushort v136, v[130:131], off
	global_load_ushort v140, v[130:131], off offset:768
	global_load_ushort v132, v[130:131], off offset:1536
	global_load_ushort v137, v[146:147], off offset:1536
	s_cmpk_gt_i32 s30, 0x7ff
	s_cselect_b64 s[2:3], -1, 0
	s_and_b32 s16, s30, 0x1ff
	s_cmp_eq_u32 s16, 0
	s_cselect_b64 s[16:17], -1, 0
	s_or_b64 s[2:3], s[2:3], s[16:17]
	v_mov_b32_e32 v1, 0
	s_and_b64 vcc, exec, s[2:3]
	v_mov_b32_e32 v130, 0
	v_mov_b32_e32 v131, 0
	s_cbranch_vccnz .LBB0_767
	s_add_i32 s2, s23, 0xfffffc78
	v_mad_i64_i32 v[130:131], s[2:3], s2, v208, v[176:177]
	global_load_ushort v1, v[130:131], off
	global_load_ushort v145, v[130:131], off offset:1536
	global_load_ushort v146, v[130:131], off offset:768
	s_waitcnt vmcnt(0)
	v_lshlrev_b32_e32 v131, 16, v1
	v_lshlrev_b32_e32 v130, 16, v145
	v_lshlrev_b32_e32 v1, 16, v146

; __device__ __forceinline__ float bf2f(bf16_t b) { return __uint_as_float(((unsigned)b) << 16); }
; __device__ __forceinline__ float sigmoidf_(float x) { return 1.f / (1.f + __expf(-x)); }
; __device__ __forceinline__ void p2_rwkv_prep(const Params& P, float* lds) {
;     ...
;             for (int tk = tg; tk < tg + 4; ++tk) {
;                 const int tok = tok0 + tk;
;                 if (tok >= NTOK) { const float* p = P.state_shift + (size_t)(tok - NTOK) * RCOLS + tid; qr = p[0]; qk = p[RW]; qv = p[2 * RW]; }
;                 const float cr = nr[tk & 3], ck = nk[tk & 3], cv = nv[tk & 3];
;                 if (tk + 4 < CT) { const bf16_t* p = prw + (size_t)(tok + 4) * RCOLS + tid; nr[tk & 3] = bf2f(p[0]); nk[tk & 3] = bf2f(p[RW]); nv[tk & 3] = bf2f(p[2 * RW]); }
;                 const float r = cr + (qr - cr) * mur, kraw = ck + (qk - ck) * muk, v = cv + (qv - cv) * muv;
;                 qr = cr; qk = ck; qv = cv;
;                 const float aw = w0c + yt[tk * 64 + cc], aa = a0c + yt[(CT + tk) * 64 + cc];
;                 const float w = __expf(-DECAY_SCALE * sigmoidf_(aw)), a = sigmoidf_(aa);
;                 const float kkv = kraw * kkc;
;                 const float n2 = wave_sum_fast(kkv * kkv);
;                 const float kk = kkv * rsqrtf(fmaxf(n2, 1e-12f));
;                 const float kmod = kraw * (1.f + (a - 1.f) * kac);
;                 const float bb = kk * a;
;                 const float br = wave_sum_fast(bb * r);
;                 ekk[tk - tg] = kk; ew[tk - tg] = w; ebb[tk - tg] = bb; ekm[tk - tg] = kmod; ewr[tk - tg] = w * r - kk * br; ev[tk - tg] = v;
;                 ebr[tk - tg] = br; ekr[tk - tg] = wave_sum_fast(kmod * r); erk[tk - tg] = wave_sum_fast(r * kmod * rkc);
.LBB0_785:
	s_or_b64 exec, exec, s[2:3]
	s_waitcnt lgkmcnt(0)
	s_cmpk_gt_i32 s30, 0x7ff
	s_cselect_b64 s[2:3], -1, 0
	s_cmpk_lt_i32 s30, 0x800
	s_cbranch_scc1 .LBB0_787
	s_add_i32 s16, s23, 0xffffbc79
	v_mad_u64_u32 v[134:135], s[16:17], s16, v210, v[178:179]
	global_load_dword v131, v[134:135], off
	global_load_dword v1, v[134:135], off offset:1536
	global_load_dword v130, v[134:135], off offset:3072
.LBB0_787:
	s_add_i32 s16, s23, 0xfffffc7d
	v_mad_u64_u32 v[136:137], s[20:21], s16, v208, v[176:177]
	ds_read2st64_b32 v[134:135], v199 offset0:32 offset1:40
	global_load_ushort v156, v[136:137], off
	global_load_ushort v158, v[136:137], off offset:768
	global_load_ushort v157, v[136:137], off offset:1536
	s_waitcnt vmcnt(5)
	v_sub_f32_e32 v131, v131, v188
	v_fma_f32 v152, v196, v131, v188
	s_waitcnt vmcnt(4)
	v_sub_f32_e32 v1, v1, v189
	s_waitcnt lgkmcnt(0)
	v_add_f32_e32 v132, v194, v135
	v_mul_f32_e32 v132, 0xbfb8aa3b, v132
	v_exp_f32_e32 v132, v132
	v_mov_b32_e32 v136, v189
	v_fmac_f32_e32 v136, v195, v1
	v_mov_b32_e32 v167, v213
	v_add_f32_e32 v131, 1.0, v132
	v_div_scale_f32 v132, s[20:21], v131, v131, 1.0
	v_rcp_f32_e32 v135, v132
	s_nop 0
	v_fma_f32 v1, -v132, v135, 1.0
	v_fmac_f32_e32 v135, v1, v135
	v_div_scale_f32 v1, vcc, 1.0, v131, 1.0
	v_mul_f32_e32 v137, v1, v135
	v_fma_f32 v138, -v132, v137, v1
	v_fmac_f32_e32 v137, v138, v135
	v_fma_f32 v1, -v132, v137, v1
	v_mul_f32_e32 v132, v193, v136
	v_mul_f32_e32 v138, v132, v132
	v_div_fmas_f32 v1, v1, v135, v137
	v_div_fixup_f32 v1, v1, v131, 1.0
	v_mov_b32_dpp v138, v138 quad_perm:[1,0,3,2] row_mask:0xf bank_mask:0xf bound_ctrl:1
	v_fmac_f32_e32 v138, v132, v132
	v_add_f32_e32 v131, -1.0, v1
	v_fma_f32 v131, v192, v131, 1.0
	v_add_f32_dpp v138, v138, v138 quad_perm:[2,3,0,1] row_mask:0xf bank_mask:0xf bound_ctrl:1
	v_mul_f32_e32 v154, v136, v131
	s_andn2_b64 vcc, exec, s[2:3]
	v_add_f32_dpp v138, v138, v138 row_ror:4 row_mask:0xf bank_mask:0xf bound_ctrl:1
	s_nop 1
	v_add_f32_dpp v138, v138, v138 row_ror:8 row_mask:0xf bank_mask:0xf bound_ctrl:1
	v_mov_b32_e32 v139, v138
	s_nop 1
	v_permlane16_swap_b32_e32 v138, v139
	v_add_f32_e32 v138, v138, v139
	v_mov_b32_e32 v139, v138
	s_nop 1
	v_permlane32_swap_b32_e32 v138, v139
	v_add_f32_e32 v138, v138, v139
	v_max_f32_e32 v138, 0x2b8cbccc, v138
	v_rsq_f32_e32 v138, v138
	s_nop 0
	v_mul_f32_e32 v132, v132, v138
	v_mul_f32_e32 v155, v1, v132
	v_mul_f32_e32 v1, v152, v155
	s_nop 1
	v_mov_b32_dpp v1, v1 quad_perm:[1,0,3,2] row_mask:0xf bank_mask:0xf bound_ctrl:1
	v_fmac_f32_e32 v1, v152, v155
	s_nop 1
	v_add_f32_dpp v1, v1, v1 quad_perm:[2,3,0,1] row_mask:0xf bank_mask:0xf bound_ctrl:1
	s_nop 1
	v_add_f32_dpp v1, v1, v1 row_ror:4 row_mask:0xf bank_mask:0xf bound_ctrl:1
	s_nop 1
	v_add_f32_dpp v1, v1, v1 row_ror:8 row_mask:0xf bank_mask:0xf bound_ctrl:1
	v_mov_b32_e32 v131, v1
	s_nop 1
	v_permlane16_swap_b32_e32 v1, v131
	v_add_f32_e32 v136, v1, v131
	v_mul_f32_e32 v1, v152, v154
	v_mov_b32_e32 v150, v136
	s_nop 1
	v_permlane32_swap_b32_e32 v136, v150
	v_mov_b32_dpp v131, v1 quad_perm:[1,0,3,2] row_mask:0xf bank_mask:0xf bound_ctrl:1
	v_fmac_f32_e32 v131, v152, v154
	s_nop 1
	v_add_f32_dpp v131, v131, v131 quad_perm:[2,3,0,1] row_mask:0xf bank_mask:0xf bound_ctrl:1
	s_nop 1
	v_add_f32_dpp v131, v131, v131 row_ror:4 row_mask:0xf bank_mask:0xf bound_ctrl:1
	s_nop 1
	v_add_f32_dpp v131, v131, v131 row_ror:8 row_mask:0xf bank_mask:0xf bound_ctrl:1
	v_mov_b32_e32 v135, v131
	s_nop 1
	v_permlane16_swap_b32_e32 v131, v135
	v_add_f32_e32 v137, v131, v135
	v_mul_f32_e32 v131, v197, v1
	v_mov_b32_e32 v151, v137
	s_nop 1
	v_permlane32_swap_b32_e32 v137, v151
	v_mov_b32_dpp v131, v131 quad_perm:[1,0,3,2] row_mask:0xf bank_mask:0xf bound_ctrl:1
	v_fmac_f32_e32 v131, v197, v1
	s_nop 1
	v_add_f32_dpp v1, v131, v131 quad_perm:[2,3,0,1] row_mask:0xf bank_mask:0xf bound_ctrl:1
	s_nop 1
	v_add_f32_dpp v1, v1, v1 row_ror:4 row_mask:0xf bank_mask:0xf bound_ctrl:1
	s_nop 1
	v_add_f32_dpp v1, v1, v1 row_ror:8 row_mask:0xf bank_mask:0xf bound_ctrl:1
	v_mov_b32_e32 v131, v1
	s_nop 1
	v_permlane16_swap_b32_e32 v1, v131
	v_add_f32_e32 v168, v1, v131
	v_mov_b32_e32 v169, v168
	s_nop 1
	v_permlane32_swap_b32_e32 v168, v169
	s_cbranch_vccnz .LBB0_789
	s_add_i32 s2, s23, 0xffffbc7a
	v_mad_u64_u32 v[138:139], s[2:3], s2, v210, v[178:179]
	global_load_dword v188, v[138:139], off
	global_load_dword v189, v[138:139], off offset:1536
	global_load_dword v167, v[138:139], off offset:3072
; __device__ __forceinline__ float bf2f(bf16_t b) { return __uint_as_float(((unsigned)b) << 16); }
; __device__ __forceinline__ float sigmoidf_(float x) { return 1.f / (1.f + __expf(-x)); }
; __device__ __forceinline__ void p2_rwkv_prep(const Params& P, float* lds) {
;     ...
;             for (int tk = tg; tk < tg + 4; ++tk) {
;                 const int tok = tok0 + tk;
;                 if (tok >= NTOK) { const float* p = P.state_shift + (size_t)(tok - NTOK) * RCOLS + tid; qr = p[0]; qk = p[RW]; qv = p[2 * RW]; }
;                 const float cr = nr[tk & 3], ck = nk[tk & 3], cv = nv[tk & 3];
;                 if (tk + 4 < CT) { const bf16_t* p = prw + (size_t)(tok + 4) * RCOLS + tid; nr[tk & 3] = bf2f(p[0]); nk[tk & 3] = bf2f(p[RW]); nv[tk & 3] = bf2f(p[2 * RW]); }
;                 const float r = cr + (qr - cr) * mur, kraw = ck + (qk - ck) * muk, v = cv + (qv - cv) * muv;
;                 qr = cr; qk = ck; qv = cv;
;                 const float aw = w0c + yt[tk * 64 + cc], aa = a0c + yt[(CT + tk) * 64 + cc];
;                 const float w = __expf(-DECAY_SCALE * sigmoidf_(aw)), a = sigmoidf_(aa);
;                 const float kkv = kraw * kkc;
;                 const float n2 = wave_sum_fast(kkv * kkv);
;                 const float kk = kkv * rsqrtf(fmaxf(n2, 1e-12f));
;                 const float kmod = kraw * (1.f + (a - 1.f) * kac);
;                 const float bb = kk * a;
;                 const float br = wave_sum_fast(bb * r);
;                 ekk[tk - tg] = kk; ew[tk - tg] = w; ebb[tk - tg] = bb; ekm[tk - tg] = kmod; ewr[tk - tg] = w * r - kk * br; ev[tk - tg] = v;
;                 ebr[tk - tg] = br; ekr[tk - tg] = wave_sum_fast(kmod * r); erk[tk - tg] = wave_sum_fast(r * kmod * rkc);
.LBB0_789:
	s_add_i32 s17, s23, 0xfffffc7e
	v_mad_u64_u32 v[140:141], s[2:3], s17, v208, v[176:177]
	ds_read2st64_b32 v[138:139], v199 offset0:33 offset1:41
	global_load_ushort v159, v[140:141], off
	global_load_ushort v161, v[140:141], off offset:768
	global_load_ushort v160, v[140:141], off offset:1536
	s_waitcnt vmcnt(5)
	v_sub_f32_e32 v131, v188, v186
	s_waitcnt vmcnt(4)
	v_sub_f32_e32 v140, v189, v187
	v_mov_b32_e32 v141, v187
	s_waitcnt lgkmcnt(0)
	v_add_f32_e32 v1, v194, v139
	v_mul_f32_e32 v1, 0xbfb8aa3b, v1
	v_exp_f32_e32 v1, v1
	v_fma_f32 v139, v196, v131, v186
	v_fmac_f32_e32 v141, v195, v140
	s_add_i32 s33, s23, 0xfffffc7b
	v_add_f32_e32 v1, 1.0, v1
	v_div_scale_f32 v131, s[2:3], v1, v1, 1.0
	v_rcp_f32_e32 v135, v131
	s_cmpk_lt_i32 s33, 0x4000
	v_mov_b32_e32 v218, v214
	v_fma_f32 v140, -v131, v135, 1.0
	v_fmac_f32_e32 v135, v140, v135
	v_div_scale_f32 v140, vcc, 1.0, v1, 1.0
	v_mul_f32_e32 v142, v140, v135
	v_fma_f32 v143, -v131, v142, v140
	v_fmac_f32_e32 v142, v143, v135
	v_fma_f32 v131, -v131, v142, v140
	v_mul_f32_e32 v140, v193, v141
	v_mul_f32_e32 v143, v140, v140
	v_div_fmas_f32 v131, v131, v135, v142
	v_div_fixup_f32 v1, v131, v1, 1.0
	v_mov_b32_dpp v143, v143 quad_perm:[1,0,3,2] row_mask:0xf bank_mask:0xf bound_ctrl:1
	v_fmac_f32_e32 v143, v140, v140
	v_add_f32_e32 v131, -1.0, v1
	v_fma_f32 v131, v192, v131, 1.0
	v_add_f32_dpp v143, v143, v143 quad_perm:[2,3,0,1] row_mask:0xf bank_mask:0xf bound_ctrl:1
	v_mul_f32_e32 v189, v141, v131
	s_nop 0
	v_add_f32_dpp v143, v143, v143 row_ror:4 row_mask:0xf bank_mask:0xf bound_ctrl:1
	s_nop 1
	v_add_f32_dpp v143, v143, v143 row_ror:8 row_mask:0xf bank_mask:0xf bound_ctrl:1
	v_mov_b32_e32 v144, v143
	s_nop 1
	v_permlane16_swap_b32_e32 v143, v144
	v_add_f32_e32 v143, v143, v144
	v_mov_b32_e32 v144, v143
	s_nop 1
	v_permlane32_swap_b32_e32 v143, v144
	v_add_f32_e32 v143, v143, v144
	v_max_f32_e32 v143, 0x2b8cbccc, v143
	v_rsq_f32_e32 v143, v143
	s_nop 0
	v_mul_f32_e32 v188, v140, v143
	v_mul_f32_e32 v217, v1, v188
	v_mul_f32_e32 v1, v139, v217
	s_nop 1
	v_mov_b32_dpp v1, v1 quad_perm:[1,0,3,2] row_mask:0xf bank_mask:0xf bound_ctrl:1
	v_fmac_f32_e32 v1, v139, v217
	s_nop 1
	v_add_f32_dpp v1, v1, v1 quad_perm:[2,3,0,1] row_mask:0xf bank_mask:0xf bound_ctrl:1
	s_nop 1
	v_add_f32_dpp v1, v1, v1 row_ror:4 row_mask:0xf bank_mask:0xf bound_ctrl:1
	s_nop 1
	v_add_f32_dpp v1, v1, v1 row_ror:8 row_mask:0xf bank_mask:0xf bound_ctrl:1
	v_mov_b32_e32 v131, v1
	s_nop 1
	v_permlane16_swap_b32_e32 v1, v131
	v_add_f32_e32 v142, v1, v131
	v_mul_f32_e32 v1, v139, v189
	v_mov_b32_e32 v144, v142
	s_nop 1
	v_permlane32_swap_b32_e32 v142, v144
	v_mov_b32_dpp v131, v1 quad_perm:[1,0,3,2] row_mask:0xf bank_mask:0xf bound_ctrl:1
	v_fmac_f32_e32 v131, v139, v189
	s_nop 1
	v_add_f32_dpp v131, v131, v131 quad_perm:[2,3,0,1] row_mask:0xf bank_mask:0xf bound_ctrl:1
	s_nop 1
	v_add_f32_dpp v131, v131, v131 row_ror:4 row_mask:0xf bank_mask:0xf bound_ctrl:1
	s_nop 1
	v_add_f32_dpp v131, v131, v131 row_ror:8 row_mask:0xf bank_mask:0xf bound_ctrl:1
	v_mov_b32_e32 v135, v131
	s_nop 1
	v_permlane16_swap_b32_e32 v131, v135
	v_add_f32_e32 v143, v131, v135
	v_mul_f32_e32 v131, v197, v1
	v_mov_b32_e32 v145, v143
	s_nop 1
	v_permlane32_swap_b32_e32 v143, v145
	v_mov_b32_dpp v131, v131 quad_perm:[1,0,3,2] row_mask:0xf bank_mask:0xf bound_ctrl:1
	v_fmac_f32_e32 v131, v197, v1
	s_nop 1
	v_add_f32_dpp v1, v131, v131 quad_perm:[2,3,0,1] row_mask:0xf bank_mask:0xf bound_ctrl:1
	s_nop 1
	v_add_f32_dpp v1, v1, v1 row_ror:4 row_mask:0xf bank_mask:0xf bound_ctrl:1
	s_nop 1
	v_add_f32_dpp v1, v1, v1 row_ror:8 row_mask:0xf bank_mask:0xf bound_ctrl:1
	v_mov_b32_e32 v131, v1
	s_nop 1
	v_permlane16_swap_b32_e32 v1, v131
	v_add_f32_e32 v219, v1, v131
	v_mov_b32_e32 v220, v219
	s_nop 1
	v_permlane32_swap_b32_e32 v219, v220
	s_cbranch_scc1 .LBB0_791
	s_add_i32 s2, s23, 0xffffbc7b
	v_mad_u64_u32 v[140:141], s[2:3], s2, v210, v[178:179]
	global_load_dword v186, v[140:141], off
	global_load_dword v187, v[140:141], off offset:1536
	global_load_dword v218, v[140:141], off offset:3072
.LBB0_791:
	s_add_i32 s20, s23, 0xfffffc7f
	v_mad_u64_u32 v[146:147], s[2:3], s20, v208, v[176:177]
	ds_read2st64_b32 v[140:141], v199 offset0:34 offset1:42
	global_load_ushort v162, v[146:147], off
	global_load_ushort v164, v[146:147], off offset:768
	global_load_ushort v163, v[146:147], off offset:1536
	s_waitcnt vmcnt(5)
	v_sub_f32_e32 v131, v186, v184
	s_waitcnt vmcnt(4)
	v_sub_f32_e32 v146, v187, v185
	v_mov_b32_e32 v147, v185
	s_waitcnt lgkmcnt(0)
; __device__ __forceinline__ float bf2f(bf16_t b) { return __uint_as_float(((unsigned)b) << 16); }
; __device__ __forceinline__ float sigmoidf_(float x) { return 1.f / (1.f + __expf(-x)); }
; __device__ __forceinline__ void p2_rwkv_prep(const Params& P, float* lds) {
;     ...
;             for (int tk = tg; tk < tg + 4; ++tk) {
;                 const int tok = tok0 + tk;
;                 if (tok >= NTOK) { const float* p = P.state_shift + (size_t)(tok - NTOK) * RCOLS + tid; qr = p[0]; qk = p[RW]; qv = p[2 * RW]; }
;                 const float cr = nr[tk & 3], ck = nk[tk & 3], cv = nv[tk & 3];
;                 if (tk + 4 < CT) { const bf16_t* p = prw + (size_t)(tok + 4) * RCOLS + tid; nr[tk & 3] = bf2f(p[0]); nk[tk & 3] = bf2f(p[RW]); nv[tk & 3] = bf2f(p[2 * RW]); }
;                 const float r = cr + (qr - cr) * mur, kraw = ck + (qk - ck) * muk, v = cv + (qv - cv) * muv;
;                 qr = cr; qk = ck; qv = cv;
;                 const float aw = w0c + yt[tk * 64 + cc], aa = a0c + yt[(CT + tk) * 64 + cc];
;                 const float w = __expf(-DECAY_SCALE * sigmoidf_(aw)), a = sigmoidf_(aa);
;                 const float kkv = kraw * kkc;
;                 const float n2 = wave_sum_fast(kkv * kkv);
;                 const float kk = kkv * rsqrtf(fmaxf(n2, 1e-12f));
;                 const float kmod = kraw * (1.f + (a - 1.f) * kac);
;                 const float bb = kk * a;
;                 const float br = wave_sum_fast(bb * r);
;                 ekk[tk - tg] = kk; ew[tk - tg] = w; ebb[tk - tg] = bb; ekm[tk - tg] = kmod; ewr[tk - tg] = w * r - kk * br; ev[tk - tg] = v;
;                 ebr[tk - tg] = br; ekr[tk - tg] = wave_sum_fast(kmod * r); erk[tk - tg] = wave_sum_fast(r * kmod * rkc);
	v_add_f32_e32 v1, v194, v141
	v_mul_f32_e32 v1, 0xbfb8aa3b, v1
	v_exp_f32_e32 v1, v1
	v_fma_f32 v141, v196, v131, v184
	v_fmac_f32_e32 v147, v195, v146
	s_add_i32 s34, s23, 0xfffffc7c
	v_add_f32_e32 v1, 1.0, v1
	v_div_scale_f32 v131, s[2:3], v1, v1, 1.0
	v_rcp_f32_e32 v135, v131
	s_cmpk_lt_i32 s34, 0x4000
	v_mov_b32_e32 v222, v216
	v_fma_f32 v146, -v131, v135, 1.0
	v_fmac_f32_e32 v135, v146, v135
	v_div_scale_f32 v146, vcc, 1.0, v1, 1.0
	v_mul_f32_e32 v148, v146, v135
	v_fma_f32 v149, -v131, v148, v146
	v_fmac_f32_e32 v148, v149, v135
	v_fma_f32 v131, -v131, v148, v146
	v_mul_f32_e32 v146, v193, v147
	v_mul_f32_e32 v149, v146, v146
	v_div_fmas_f32 v131, v131, v135, v148
	v_div_fixup_f32 v1, v131, v1, 1.0
	v_mov_b32_dpp v149, v149 quad_perm:[1,0,3,2] row_mask:0xf bank_mask:0xf bound_ctrl:1
	v_fmac_f32_e32 v149, v146, v146
	v_add_f32_e32 v131, -1.0, v1
	v_fma_f32 v131, v192, v131, 1.0
	v_add_f32_dpp v149, v149, v149 quad_perm:[2,3,0,1] row_mask:0xf bank_mask:0xf bound_ctrl:1
	v_mul_f32_e32 v187, v147, v131
	s_nop 0
	v_add_f32_dpp v149, v149, v149 row_ror:4 row_mask:0xf bank_mask:0xf bound_ctrl:1
	s_nop 1
	v_add_f32_dpp v149, v149, v149 row_ror:8 row_mask:0xf bank_mask:0xf bound_ctrl:1
	v_mov_b32_e32 v153, v149
	s_nop 1
	v_permlane16_swap_b32_e32 v149, v153
	v_add_f32_e32 v149, v149, v153
	v_mov_b32_e32 v153, v149
	s_nop 1
	v_permlane32_swap_b32_e32 v149, v153
	v_add_f32_e32 v149, v149, v153
	v_max_f32_e32 v149, 0x2b8cbccc, v149
	v_rsq_f32_e32 v149, v149
	s_nop 0
	v_mul_f32_e32 v186, v146, v149
	v_mul_f32_e32 v221, v1, v186
	v_mul_f32_e32 v1, v141, v221
	s_nop 1
	v_mov_b32_dpp v1, v1 quad_perm:[1,0,3,2] row_mask:0xf bank_mask:0xf bound_ctrl:1
	v_fmac_f32_e32 v1, v141, v221
	s_nop 1
	v_add_f32_dpp v1, v1, v1 quad_perm:[2,3,0,1] row_mask:0xf bank_mask:0xf bound_ctrl:1
	s_nop 1
	v_add_f32_dpp v1, v1, v1 row_ror:4 row_mask:0xf bank_mask:0xf bound_ctrl:1
	s_nop 1
	v_add_f32_dpp v1, v1, v1 row_ror:8 row_mask:0xf bank_mask:0xf bound_ctrl:1
	v_mov_b32_e32 v131, v1
	s_nop 1
	v_permlane16_swap_b32_e32 v1, v131
	v_add_f32_e32 v146, v1, v131
	v_mul_f32_e32 v1, v141, v187
	v_mov_b32_e32 v148, v146
	s_nop 1
	v_permlane32_swap_b32_e32 v146, v148
	v_mov_b32_dpp v131, v1 quad_perm:[1,0,3,2] row_mask:0xf bank_mask:0xf bound_ctrl:1
	v_fmac_f32_e32 v131, v141, v187
	s_nop 1
	v_add_f32_dpp v131, v131, v131 quad_perm:[2,3,0,1] row_mask:0xf bank_mask:0xf bound_ctrl:1
	s_nop 1
	v_add_f32_dpp v131, v131, v131 row_ror:4 row_mask:0xf bank_mask:0xf bound_ctrl:1
	s_nop 1
	v_add_f32_dpp v131, v131, v131 row_ror:8 row_mask:0xf bank_mask:0xf bound_ctrl:1
	v_mov_b32_e32 v135, v131
	s_nop 1
	v_permlane16_swap_b32_e32 v131, v135
	v_add_f32_e32 v147, v131, v135
	v_mul_f32_e32 v131, v197, v1
	v_mov_b32_e32 v149, v147
	s_nop 1
	v_permlane32_swap_b32_e32 v147, v149
	v_mov_b32_dpp v131, v131 quad_perm:[1,0,3,2] row_mask:0xf bank_mask:0xf bound_ctrl:1
	v_fmac_f32_e32 v131, v197, v1
	s_nop 1
	v_add_f32_dpp v1, v131, v131 quad_perm:[2,3,0,1] row_mask:0xf bank_mask:0xf bound_ctrl:1
	s_nop 1
	v_add_f32_dpp v1, v1, v1 row_ror:4 row_mask:0xf bank_mask:0xf bound_ctrl:1
	s_nop 1
	v_add_f32_dpp v1, v1, v1 row_ror:8 row_mask:0xf bank_mask:0xf bound_ctrl:1
	v_mov_b32_e32 v131, v1
	s_nop 1
	v_permlane16_swap_b32_e32 v1, v131
	v_add_f32_e32 v223, v1, v131
	v_mov_b32_e32 v224, v223
	s_nop 1
	v_permlane32_swap_b32_e32 v223, v224
	s_cbranch_scc1 .LBB0_793
	s_add_i32 s2, s23, 0xffffbc7c
	v_mad_u64_u32 v[226:227], s[2:3], s2, v210, v[178:179]
	global_load_dword v184, v[226:227], off
	global_load_dword v185, v[226:227], off offset:1536
	global_load_dword v222, v[226:227], off offset:3072
; __device__ __forceinline__ float bf2f(bf16_t b) { return __uint_as_float(((unsigned)b) << 16); }
; __device__ __forceinline__ void p2_rwkv_prep(const Params& P, float* lds) {
;     ...
;             for (int tk = tg; tk < tg + 4; ++tk) {
;                 const int tok = tok0 + tk;
;                 if (tok >= NTOK) { const float* p = P.state_shift + (size_t)(tok - NTOK) * RCOLS + tid; qr = p[0]; qk = p[RW]; qv = p[2 * RW]; }
;                 const float cr = nr[tk & 3], ck = nk[tk & 3], cv = nv[tk & 3];
;                 if (tk + 4 < CT) { const bf16_t* p = prw + (size_t)(tok + 4) * RCOLS + tid; nr[tk & 3] = bf2f(p[0]); nk[tk & 3] = bf2f(p[RW]); nv[tk & 3] = bf2f(p[2 * RW]); }
;                 const float r = cr + (qr - cr) * mur, kraw = ck + (qk - ck) * muk, v = cv + (qv - cv) * muv;
;                 qr = cr; qk = ck; qv = cv;
;                 const float aw = w0c + yt[tk * 64 + cc], aa = a0c + yt[(CT + tk) * 64 + cc];
;                 const float w = __expf(-DECAY_SCALE * sigmoidf_(aw)), a = sigmoidf_(aa);
;                 const float kkv = kraw * kkc;
;                 const float n2 = wave_sum_fast(kkv * kkv);
;                 const float kk = kkv * rsqrtf(fmaxf(n2, 1e-12f));
;                 const float kmod = kraw * (1.f + (a - 1.f) * kac);
;                 const float bb = kk * a;
;                 const float br = wave_sum_fast(bb * r);
;                 ekk[tk - tg] = kk; ew[tk - tg] = w; ebb[tk - tg] = bb; ekm[tk - tg] = kmod; ewr[tk - tg] = w * r - kk * br; ev[tk - tg] = v;
;                 ebr[tk - tg] = br; ekr[tk - tg] = wave_sum_fast(kmod * r); erk[tk - tg] = wave_sum_fast(r * kmod * rkc);
;             }
; #pragma unroll
;             for (int tk = tg; tk < tg + 4; ++tk) {
;                 float* blk = RSB + ((size_t)(tok0 + tk) * RH + h) * RSB_BLK;
;                 float* oq = ot + (tk & 1) * 384;
;                 oq[cc] = ekk[tk - tg]; oq[64 + cc] = ew[tk - tg]; oq[128 + cc] = ebb[tk - tg]; oq[192 + cc] = ekm[tk - tg]; oq[256 + cc] = ewr[tk - tg]; oq[320 + cc] = ev[tk - tg];
;                 __builtin_amdgcn_wave_barrier();
;                 *(float4*)(blk + 4 * lane) = *(const float4*)(oq + 4 * lane);
;                 if (lane < 32) *(float4*)(blk + 256 + 4 * lane) = *(const float4*)(oq + 256 + 4 * lane);
;                 if (lane == 0) *(float4*)(blk + 384) = make_float4(ebr[tk - tg], ekr[tk - tg], erk[tk - tg], 0.f);
.LBB0_793:
	v_add_f32_e32 v1, v190, v134
	v_mul_f32_e32 v1, 0xbfb8aa3b, v1
	v_exp_f32_e32 v1, v1
	v_sub_f32_e32 v153, v130, v213
	v_pk_add_f32 v[134:135], v[136:137], v[150:151]
	s_add_i32 s21, s23, 0xfffffc80
	v_add_f32_e32 v1, 1.0, v1
	v_div_scale_f32 v130, s[2:3], v1, v1, 1.0
	v_rcp_f32_e32 v131, v130
	v_div_scale_f32 v136, vcc, 1.0, v1, 1.0
	s_waitcnt vmcnt(1)
	v_sub_f32_e32 v151, v185, v183
	v_fma_f32 v137, -v130, v131, 1.0
	v_fmac_f32_e32 v131, v137, v131
	v_mul_f32_e32 v137, v136, v131
	v_fma_f32 v150, -v130, v137, v136
	v_fmac_f32_e32 v137, v150, v131
	v_fma_f32 v130, -v130, v137, v136
	v_div_fmas_f32 v130, v130, v131, v137
	v_div_fixup_f32 v1, v130, v1, 1.0
	v_mul_f32_e32 v1, 0xbf1b4598, v1
	v_mul_f32_e32 v1, 0x3fb8aa3b, v1
	ds_read2st64_b32 v[130:131], v199 offset0:35 offset1:43
	v_exp_f32_e32 v228, v1
	v_mul_f32_e32 v1, v132, v134
	v_mad_u64_u32 v[136:137], s[2:3], s21, v208, v[176:177]
	v_fma_f32 v229, v152, v228, -v1
	s_waitcnt lgkmcnt(0)
	v_add_f32_e32 v1, v194, v131
	v_mul_f32_e32 v1, 0xbfb8aa3b, v1
	v_exp_f32_e32 v150, v1
	global_load_ushort v165, v[136:137], off
	global_load_ushort v166, v[136:137], off offset:768
	global_load_ushort v1, v[136:137], off offset:1536
	v_mov_b32_e32 v152, v183
	v_fmac_f32_e32 v152, v195, v151
	v_add_f32_e32 v136, 1.0, v150
	v_div_scale_f32 v137, s[2:3], v136, v136, 1.0
	v_rcp_f32_e32 v150, v137
	v_fmac_f32_e32 v213, v191, v153
	v_sub_f32_e32 v131, v184, v182
	v_fma_f32 v131, v196, v131, v182
	v_fma_f32 v151, -v137, v150, 1.0
	v_fmac_f32_e32 v150, v151, v150
	v_div_scale_f32 v151, vcc, 1.0, v136, 1.0
	v_mul_f32_e32 v153, v151, v150
	v_fma_f32 v184, -v137, v153, v151
	v_fmac_f32_e32 v153, v184, v150
	v_fma_f32 v137, -v137, v153, v151
	v_mul_f32_e32 v151, v193, v152
	v_mul_f32_e32 v184, v151, v151
	v_div_fmas_f32 v137, v137, v150, v153
	v_div_fixup_f32 v136, v137, v136, 1.0
	v_mov_b32_dpp v184, v184 quad_perm:[1,0,3,2] row_mask:0xf bank_mask:0xf bound_ctrl:1
	v_fmac_f32_e32 v184, v151, v151
	v_add_f32_e32 v137, -1.0, v136
	v_fma_f32 v137, v192, v137, 1.0
	v_add_f32_dpp v184, v184, v184 quad_perm:[2,3,0,1] row_mask:0xf bank_mask:0xf bound_ctrl:1
	s_mul_hi_u32 s35, s31, 6
	s_mul_i32 s31, s31, 6
	v_add_f32_dpp v184, v184, v184 row_ror:4 row_mask:0xf bank_mask:0xf bound_ctrl:1
	v_mul_f32_e32 v253, v132, v255
	v_mul_f32_e32 v254, v228, v255
	ds_write2st64_b32 v200, v253, v254 offset0:160 offset1:161
	v_mul_f32_e32 v253, v229, v255
	ds_write2st64_b32 v200, v253, v213 offset0:164 offset1:165
	v_cndmask_b32_e64 v255, v254, 1.0, s[98:99]
	v_rcp_f32_e32 v254, v255
	s_nop 0
	v_mul_f32_e32 v253, v155, v254
	v_mul_f32_e32 v254, v154, v254
	ds_write2st64_b32 v200, v253, v254 offset0:162 offset1:163
	v_add_f32_dpp v184, v184, v184 row_ror:8 row_mask:0xf bank_mask:0xf bound_ctrl:1
	v_mov_b32_e32 v185, v184
	s_nop 1
	v_permlane16_swap_b32_e32 v184, v185
	v_add_f32_e32 v184, v184, v185
	v_mov_b32_e32 v185, v184
	s_nop 1
	v_permlane32_swap_b32_e32 v184, v185
	v_add_f32_e32 v184, v184, v185
	v_max_f32_e32 v184, 0x2b8cbccc, v184
	v_rsq_f32_e32 v184, v184
	v_mul_f32_e32 v185, v152, v137
	ds_read_b128 v[228:231], v201
	v_or_b32_e32 v232, s31, v170
	v_mul_f32_e32 v184, v151, v184
	v_mul_f32_e32 v225, v136, v184
	v_mul_f32_e32 v136, v131, v225
	v_lshlrev_b32_e32 v132, 2, v172
	s_nop 0
	v_mov_b32_dpp v136, v136 quad_perm:[1,0,3,2] row_mask:0xf bank_mask:0xf bound_ctrl:1
	v_fmac_f32_e32 v136, v131, v225
	s_nop 1
	v_add_f32_dpp v136, v136, v136 quad_perm:[2,3,0,1] row_mask:0xf bank_mask:0xf bound_ctrl:1
	s_nop 1
	v_add_f32_dpp v136, v136, v136 row_ror:4 row_mask:0xf bank_mask:0xf bound_ctrl:1
	s_nop 1
	v_add_f32_dpp v136, v136, v136 row_ror:8 row_mask:0xf bank_mask:0xf bound_ctrl:1
	v_mov_b32_e32 v137, v136
	s_nop 1
	v_permlane16_swap_b32_e32 v136, v137
	v_add_f32_e32 v150, v136, v137
	v_mul_f32_e32 v136, v131, v185
	v_mov_b32_e32 v152, v150
	s_nop 1
	v_permlane32_swap_b32_e32 v150, v152
	v_mov_b32_dpp v137, v136 quad_perm:[1,0,3,2] row_mask:0xf bank_mask:0xf bound_ctrl:1
	v_fmac_f32_e32 v137, v131, v185
	s_nop 1
	v_add_f32_dpp v137, v137, v137 quad_perm:[2,3,0,1] row_mask:0xf bank_mask:0xf bound_ctrl:1
	s_nop 1
	v_add_f32_dpp v137, v137, v137 row_ror:4 row_mask:0xf bank_mask:0xf bound_ctrl:1
	s_nop 1
	v_add_f32_dpp v137, v137, v137 row_ror:8 row_mask:0xf bank_mask:0xf bound_ctrl:1
	v_mov_b32_e32 v151, v137
	s_nop 1
	v_permlane16_swap_b32_e32 v137, v151
	v_add_f32_e32 v151, v137, v151
	v_mul_f32_e32 v137, v197, v136
	v_mov_b32_e32 v153, v151
	s_nop 1
	v_permlane32_swap_b32_e32 v151, v153
	v_mov_b32_dpp v137, v137 quad_perm:[1,0,3,2] row_mask:0xf bank_mask:0xf bound_ctrl:1
	v_fmac_f32_e32 v137, v197, v136
	s_nop 1
	v_add_f32_dpp v136, v137, v137 quad_perm:[2,3,0,1] row_mask:0xf bank_mask:0xf bound_ctrl:1
	s_nop 1
	v_add_f32_dpp v136, v136, v136 row_ror:4 row_mask:0xf bank_mask:0xf bound_ctrl:1
	s_nop 1
	v_add_f32_dpp v136, v136, v136 row_ror:8 row_mask:0xf bank_mask:0xf bound_ctrl:1
	v_mov_b32_e32 v137, v136
	s_nop 1
	v_permlane16_swap_b32_e32 v136, v137
	v_add_f32_e32 v226, v136, v137
	v_mov_b64_e32 v[136:137], s[18:19]
	v_mad_u64_u32 v[154:155], s[2:3], v232, s25, v[136:137]
	v_mov_b32_e32 v227, v226
	v_mad_u32_u24 v155, s35, v211, v155
	s_nop 0
	v_permlane32_swap_b32_e32 v226, v227
	v_lshl_add_u64 v[136:137], v[154:155], 0, v[132:133]
	s_waitcnt lgkmcnt(0)
	global_store_dwordx4 v[136:137], v[228:231], off
	s_and_saveexec_b64 s[2:3], s[10:11]
	s_cbranch_execz .LBB0_795
	ds_read_b128 v[228:231], v202
	s_waitcnt lgkmcnt(0)
	global_store_dwordx4 v[136:137], v[228:231], off offset:1024

; __device__ __forceinline__ float sigmoidf_(float x) { return 1.f / (1.f + __expf(-x)); }
; __device__ __forceinline__ void p2_rwkv_prep(const Params& P, float* lds) {
;     ...
;                 const float aw = w0c + yt[tk * 64 + cc], aa = a0c + yt[(CT + tk) * 64 + cc];
;                 const float w = __expf(-DECAY_SCALE * sigmoidf_(aw)), a = sigmoidf_(aa);
;                 const float kkv = kraw * kkc;
;                 const float n2 = wave_sum_fast(kkv * kkv);
;                 const float kk = kkv * rsqrtf(fmaxf(n2, 1e-12f));
;                 const float kmod = kraw * (1.f + (a - 1.f) * kac);
;                 const float bb = kk * a;
;                 const float br = wave_sum_fast(bb * r);
;                 ekk[tk - tg] = kk; ew[tk - tg] = w; ebb[tk - tg] = bb; ekm[tk - tg] = kmod; ewr[tk - tg] = w * r - kk * br; ev[tk - tg] = v;
;                 ebr[tk - tg] = br; ekr[tk - tg] = wave_sum_fast(kmod * r); erk[tk - tg] = wave_sum_fast(r * kmod * rkc);
;             }
; #pragma unroll
;             for (int tk = tg; tk < tg + 4; ++tk) {
;                 float* blk = RSB + ((size_t)(tok0 + tk) * RH + h) * RSB_BLK;
;                 float* oq = ot + (tk & 1) * 384;
;                 oq[cc] = ekk[tk - tg]; oq[64 + cc] = ew[tk - tg]; oq[128 + cc] = ebb[tk - tg]; oq[192 + cc] = ekm[tk - tg]; oq[256 + cc] = ewr[tk - tg]; oq[320 + cc] = ev[tk - tg];
;                 __builtin_amdgcn_wave_barrier();
;                 *(float4*)(blk + 4 * lane) = *(const float4*)(oq + 4 * lane);
;                 if (lane < 32) *(float4*)(blk + 256 + 4 * lane) = *(const float4*)(oq + 256 + 4 * lane);
;                 if (lane == 0) *(float4*)(blk + 384) = make_float4(ebr[tk - tg], ekr[tk - tg], erk[tk - tg], 0.f);
.LBB0_797:
	s_or_b64 exec, exec, s[2:3]
	s_nop 0
	v_add_f32_e32 v134, v190, v138
	v_mul_f32_e32 v134, 0xbfb8aa3b, v134
	v_exp_f32_e32 v134, v134
	v_sub_f32_e32 v136, v167, v214
	v_fmac_f32_e32 v214, v191, v136
	v_add_f32_e32 v137, 1.0, v134
	v_div_scale_f32 v138, s[2:3], v137, v137, 1.0
	v_rcp_f32_e32 v154, v138
	v_pk_add_f32 v[134:135], v[142:143], v[144:145]
	v_div_scale_f32 v142, vcc, 1.0, v137, 1.0
	v_fma_f32 v143, -v138, v154, 1.0
	v_fmac_f32_e32 v154, v143, v154
	v_mul_f32_e32 v143, v142, v154
	v_fma_f32 v144, -v138, v143, v142
	v_fmac_f32_e32 v143, v144, v154
	v_fma_f32 v138, -v138, v143, v142
	v_div_fmas_f32 v138, v138, v154, v143
	v_div_fixup_f32 v137, v138, v137, 1.0
	v_mul_f32_e32 v137, 0xbf1b4598, v137
	v_mul_f32_e32 v137, 0x3fb8aa3b, v137
	v_exp_f32_e32 v142, v137
	v_mul_f32_e32 v136, v188, v134
	s_add_i32 s2, s23, 0xfffffc7a
	v_fma_f32 v143, v139, v142, -v136
	v_mul_f32_e32 v253, v188, v255
	v_mul_f32_e32 v254, v142, v255
	ds_write2st64_b32 v203, v253, v254 offset0:166 offset1:167
	v_mul_f32_e32 v253, v143, v255
	ds_write2st64_b32 v203, v253, v214 offset0:170 offset1:171
	v_cndmask_b32_e64 v255, v254, 1.0, s[98:99]
	v_rcp_f32_e32 v254, v255
	s_nop 0
	v_mul_f32_e32 v253, v217, v254
	v_mul_f32_e32 v254, v189, v254
	ds_write2st64_b32 v203, v253, v254 offset0:168 offset1:169
	ds_read_b128 v[142:145], v204
	v_mad_u64_u32 v[136:137], s[2:3], s2, 6, v[170:171]
	v_mov_b64_e32 v[138:139], s[18:19]
	v_mad_u64_u32 v[138:139], s[2:3], v136, s25, v[138:139]
	v_mad_u32_u24 v139, v137, s25, v139
	v_lshl_add_u64 v[136:137], v[138:139], 0, v[132:133]
	s_waitcnt lgkmcnt(0)
	global_store_dwordx4 v[136:137], v[142:145], off
	s_and_saveexec_b64 s[2:3], s[10:11]
	s_cbranch_execz .LBB0_799
	ds_read_b128 v[142:145], v205
	s_waitcnt lgkmcnt(0)
	global_store_dwordx4 v[136:137], v[142:145], off offset:1024

; __device__ __forceinline__ float bf2f(bf16_t b) { return __uint_as_float(((unsigned)b) << 16); }
; __device__ __forceinline__ float sigmoidf_(float x) { return 1.f / (1.f + __expf(-x)); }
; __device__ __forceinline__ void p2_rwkv_prep(const Params& P, float* lds) {
;     ...
;             for (int tk = tg; tk < tg + 4; ++tk) {
;                 const int tok = tok0 + tk;
;                 if (tok >= NTOK) { const float* p = P.state_shift + (size_t)(tok - NTOK) * RCOLS + tid; qr = p[0]; qk = p[RW]; qv = p[2 * RW]; }
;                 const float cr = nr[tk & 3], ck = nk[tk & 3], cv = nv[tk & 3];
;                 if (tk + 4 < CT) { const bf16_t* p = prw + (size_t)(tok + 4) * RCOLS + tid; nr[tk & 3] = bf2f(p[0]); nk[tk & 3] = bf2f(p[RW]); nv[tk & 3] = bf2f(p[2 * RW]); }
;                 const float r = cr + (qr - cr) * mur, kraw = ck + (qk - ck) * muk, v = cv + (qv - cv) * muv;
;                 qr = cr; qk = ck; qv = cv;
;                 const float aw = w0c + yt[tk * 64 + cc], aa = a0c + yt[(CT + tk) * 64 + cc];
;                 const float w = __expf(-DECAY_SCALE * sigmoidf_(aw)), a = sigmoidf_(aa);
;                 const float kkv = kraw * kkc;
;                 const float n2 = wave_sum_fast(kkv * kkv);
;                 const float kk = kkv * rsqrtf(fmaxf(n2, 1e-12f));
;                 const float kmod = kraw * (1.f + (a - 1.f) * kac);
;                 const float bb = kk * a;
;                 const float br = wave_sum_fast(bb * r);
;                 ekk[tk - tg] = kk; ew[tk - tg] = w; ebb[tk - tg] = bb; ekm[tk - tg] = kmod; ewr[tk - tg] = w * r - kk * br; ev[tk - tg] = v;
;                 ebr[tk - tg] = br; ekr[tk - tg] = wave_sum_fast(kmod * r); erk[tk - tg] = wave_sum_fast(r * kmod * rkc);
.LBB0_809:
	s_or_b64 exec, exec, s[2:3]
	s_cmpk_lt_i32 s16, 0x4000
	s_cbranch_scc1 .LBB0_811
	s_add_i32 s2, s23, 0xffffbc7d
	v_mad_u64_u32 v[130:131], s[2:3], s2, v210, v[178:179]
	global_load_dword v182, v[130:131], off
	global_load_dword v183, v[130:131], off offset:1536
	global_load_dword v215, v[130:131], off offset:3072
.LBB0_811:
	ds_read2st64_b32 v[134:135], v199 offset0:36 offset1:44
	v_lshlrev_b32_e32 v188, 16, v156
	s_waitcnt vmcnt(2)
	v_sub_f32_e32 v131, v182, v188
	v_fma_f32 v152, v196, v131, v188
	v_lshlrev_b32_e32 v189, 16, v158
	s_waitcnt lgkmcnt(0)
	v_add_f32_e32 v130, v194, v135
	v_mul_f32_e32 v130, 0xbfb8aa3b, v130
	v_exp_f32_e32 v130, v130
	s_waitcnt vmcnt(1)
	v_sub_f32_e32 v135, v183, v189
	v_fma_f32 v135, v195, v135, v189
	v_lshlrev_b32_e32 v213, 16, v157
	v_add_f32_e32 v130, 1.0, v130
	v_div_scale_f32 v131, s[2:3], v130, v130, 1.0
	v_rcp_f32_e32 v136, v131
	v_div_scale_f32 v137, vcc, 1.0, v130, 1.0
	s_cmpk_lt_i32 s17, 0x4000
	v_fma_f32 v138, -v131, v136, 1.0
	v_fmac_f32_e32 v136, v138, v136
	v_mul_f32_e32 v138, v137, v136
	v_fma_f32 v139, -v131, v138, v137
	v_fmac_f32_e32 v138, v139, v136
	v_fma_f32 v131, -v131, v138, v137
	v_mul_f32_e32 v137, v193, v135
	v_mul_f32_e32 v139, v137, v137
	v_div_fmas_f32 v131, v131, v136, v138
	v_div_fixup_f32 v130, v131, v130, 1.0
	v_mov_b32_dpp v139, v139 quad_perm:[1,0,3,2] row_mask:0xf bank_mask:0xf bound_ctrl:1
	v_fmac_f32_e32 v139, v137, v137
	v_add_f32_e32 v131, -1.0, v130
	v_fma_f32 v131, v192, v131, 1.0
	v_add_f32_dpp v139, v139, v139 quad_perm:[2,3,0,1] row_mask:0xf bank_mask:0xf bound_ctrl:1
	v_mul_f32_e32 v155, v135, v131
	v_mov_b32_e32 v157, v213
	v_add_f32_dpp v139, v139, v139 row_ror:4 row_mask:0xf bank_mask:0xf bound_ctrl:1
	v_mov_b32_e32 v138, v188
	s_nop 0
	v_add_f32_dpp v139, v139, v139 row_ror:8 row_mask:0xf bank_mask:0xf bound_ctrl:1
	v_mov_b32_e32 v140, v139
	s_nop 1
	v_permlane16_swap_b32_e32 v139, v140
	v_add_f32_e32 v139, v139, v140
	v_mov_b32_e32 v140, v139
	s_nop 1
	v_permlane32_swap_b32_e32 v139, v140
	v_add_f32_e32 v139, v139, v140
	v_max_f32_e32 v139, 0x2b8cbccc, v139
	v_rsq_f32_e32 v139, v139
	s_nop 0
	v_mul_f32_e32 v154, v137, v139
	v_mul_f32_e32 v156, v130, v154
	v_mul_f32_e32 v130, v152, v156
	s_nop 1
	v_mov_b32_dpp v130, v130 quad_perm:[1,0,3,2] row_mask:0xf bank_mask:0xf bound_ctrl:1
	v_fmac_f32_e32 v130, v152, v156
	s_nop 1
	v_add_f32_dpp v130, v130, v130 quad_perm:[2,3,0,1] row_mask:0xf bank_mask:0xf bound_ctrl:1
	s_nop 1
	v_add_f32_dpp v130, v130, v130 row_ror:4 row_mask:0xf bank_mask:0xf bound_ctrl:1
	s_nop 1
	v_add_f32_dpp v130, v130, v130 row_ror:8 row_mask:0xf bank_mask:0xf bound_ctrl:1
	v_mov_b32_e32 v131, v130
	s_nop 1
	v_permlane16_swap_b32_e32 v130, v131
	v_add_f32_e32 v136, v130, v131
	v_mul_f32_e32 v130, v152, v155
	v_mov_b32_e32 v148, v136
	s_nop 1
	v_permlane32_swap_b32_e32 v136, v148
	v_mov_b32_dpp v131, v130 quad_perm:[1,0,3,2] row_mask:0xf bank_mask:0xf bound_ctrl:1
	v_fmac_f32_e32 v131, v152, v155
	s_nop 1
	v_add_f32_dpp v131, v131, v131 quad_perm:[2,3,0,1] row_mask:0xf bank_mask:0xf bound_ctrl:1
	s_nop 1
	v_add_f32_dpp v131, v131, v131 row_ror:4 row_mask:0xf bank_mask:0xf bound_ctrl:1
	s_nop 1
	v_add_f32_dpp v131, v131, v131 row_ror:8 row_mask:0xf bank_mask:0xf bound_ctrl:1
	v_mov_b32_e32 v135, v131
	s_nop 1
	v_permlane16_swap_b32_e32 v131, v135
	v_add_f32_e32 v137, v131, v135
	v_mul_f32_e32 v131, v197, v130
	v_mov_b32_e32 v149, v137
	s_nop 1
	v_permlane32_swap_b32_e32 v137, v149
	v_mov_b32_dpp v131, v131 quad_perm:[1,0,3,2] row_mask:0xf bank_mask:0xf bound_ctrl:1
	v_fmac_f32_e32 v131, v197, v130
	v_mov_b32_e32 v135, v189
	s_nop 0
	v_add_f32_dpp v130, v131, v131 quad_perm:[2,3,0,1] row_mask:0xf bank_mask:0xf bound_ctrl:1
	s_nop 1
	v_add_f32_dpp v130, v130, v130 row_ror:4 row_mask:0xf bank_mask:0xf bound_ctrl:1
	s_nop 1
	v_add_f32_dpp v130, v130, v130 row_ror:8 row_mask:0xf bank_mask:0xf bound_ctrl:1
	v_mov_b32_e32 v131, v130
	s_nop 1
	v_permlane16_swap_b32_e32 v130, v131
	v_add_f32_e32 v158, v130, v131
	v_mov_b32_e32 v167, v158
	s_nop 1
	v_permlane32_swap_b32_e32 v158, v167
	s_cbranch_scc1 .LBB0_813
	s_add_i32 s2, s23, 0xffffbc7e
	v_mad_u64_u32 v[130:131], s[2:3], s2, v210, v[178:179]
	global_load_dword v138, v[130:131], off
	global_load_dword v135, v[130:131], off offset:1536
	global_load_dword v157, v[130:131], off offset:3072
; __device__ __forceinline__ float bf2f(bf16_t b) { return __uint_as_float(((unsigned)b) << 16); }
; __device__ __forceinline__ float sigmoidf_(float x) { return 1.f / (1.f + __expf(-x)); }
; __device__ __forceinline__ void p2_rwkv_prep(const Params& P, float* lds) {
;     ...
;             for (int tk = tg; tk < tg + 4; ++tk) {
;                 const int tok = tok0 + tk;
;                 if (tok >= NTOK) { const float* p = P.state_shift + (size_t)(tok - NTOK) * RCOLS + tid; qr = p[0]; qk = p[RW]; qv = p[2 * RW]; }
;                 const float cr = nr[tk & 3], ck = nk[tk & 3], cv = nv[tk & 3];
;                 if (tk + 4 < CT) { const bf16_t* p = prw + (size_t)(tok + 4) * RCOLS + tid; nr[tk & 3] = bf2f(p[0]); nk[tk & 3] = bf2f(p[RW]); nv[tk & 3] = bf2f(p[2 * RW]); }
;                 const float r = cr + (qr - cr) * mur, kraw = ck + (qk - ck) * muk, v = cv + (qv - cv) * muv;
;                 qr = cr; qk = ck; qv = cv;
;                 const float aw = w0c + yt[tk * 64 + cc], aa = a0c + yt[(CT + tk) * 64 + cc];
;                 const float w = __expf(-DECAY_SCALE * sigmoidf_(aw)), a = sigmoidf_(aa);
;                 const float kkv = kraw * kkc;
;                 const float n2 = wave_sum_fast(kkv * kkv);
;                 const float kk = kkv * rsqrtf(fmaxf(n2, 1e-12f));
;                 const float kmod = kraw * (1.f + (a - 1.f) * kac);
;                 const float bb = kk * a;
;                 const float br = wave_sum_fast(bb * r);
;                 ekk[tk - tg] = kk; ew[tk - tg] = w; ebb[tk - tg] = bb; ekm[tk - tg] = kmod; ewr[tk - tg] = w * r - kk * br; ev[tk - tg] = v;
;                 ebr[tk - tg] = br; ekr[tk - tg] = wave_sum_fast(kmod * r); erk[tk - tg] = wave_sum_fast(r * kmod * rkc);
.LBB0_813:
	ds_read2st64_b32 v[130:131], v199 offset0:37 offset1:45
	v_lshlrev_b32_e32 v186, 16, v159
	v_lshlrev_b32_e32 v187, 16, v161
	s_waitcnt vmcnt(1)
	v_sub_f32_e32 v135, v135, v187
	v_fma_f32 v135, v195, v135, v187
	s_waitcnt lgkmcnt(0)
	v_add_f32_e32 v131, v194, v131
	v_mul_f32_e32 v131, 0xbfb8aa3b, v131
	v_exp_f32_e32 v139, v131
	v_sub_f32_e32 v131, v138, v186
	v_fma_f32 v131, v196, v131, v186
	v_lshlrev_b32_e32 v214, 16, v160
	v_add_f32_e32 v138, 1.0, v139
	v_div_scale_f32 v139, s[2:3], v138, v138, 1.0
	v_rcp_f32_e32 v140, v139
	v_div_scale_f32 v141, vcc, 1.0, v138, 1.0
	s_cmpk_lt_i32 s20, 0x4000
	v_fma_f32 v142, -v139, v140, 1.0
	v_fmac_f32_e32 v140, v142, v140
	v_mul_f32_e32 v142, v141, v140
	v_fma_f32 v143, -v139, v142, v141
	v_fmac_f32_e32 v142, v143, v140
	v_fma_f32 v139, -v139, v142, v141
	v_mul_f32_e32 v141, v193, v135
	v_mul_f32_e32 v143, v141, v141
	v_div_fmas_f32 v139, v139, v140, v142
	v_div_fixup_f32 v138, v139, v138, 1.0
	v_mov_b32_dpp v143, v143 quad_perm:[1,0,3,2] row_mask:0xf bank_mask:0xf bound_ctrl:1
	v_fmac_f32_e32 v143, v141, v141
	v_add_f32_e32 v139, -1.0, v138
	v_fma_f32 v139, v192, v139, 1.0
	v_add_f32_dpp v143, v143, v143 quad_perm:[2,3,0,1] row_mask:0xf bank_mask:0xf bound_ctrl:1
	v_mul_f32_e32 v160, v135, v139
	v_mov_b32_e32 v168, v214
	v_add_f32_dpp v143, v143, v143 row_ror:4 row_mask:0xf bank_mask:0xf bound_ctrl:1
	s_nop 1
	v_add_f32_dpp v143, v143, v143 row_ror:8 row_mask:0xf bank_mask:0xf bound_ctrl:1
	v_mov_b32_e32 v144, v143
	s_nop 1
	v_permlane16_swap_b32_e32 v143, v144
	v_add_f32_e32 v143, v143, v144
	v_mov_b32_e32 v144, v143
	s_nop 1
	v_permlane32_swap_b32_e32 v143, v144
	v_add_f32_e32 v143, v143, v144
	v_max_f32_e32 v143, 0x2b8cbccc, v143
	v_rsq_f32_e32 v143, v143
	v_mov_b32_e32 v144, v186
	v_mul_f32_e32 v159, v141, v143
	v_mul_f32_e32 v161, v138, v159
	v_mul_f32_e32 v135, v131, v161
	s_nop 1
	v_mov_b32_dpp v135, v135 quad_perm:[1,0,3,2] row_mask:0xf bank_mask:0xf bound_ctrl:1
	v_fmac_f32_e32 v135, v131, v161
	s_nop 1
	v_add_f32_dpp v135, v135, v135 quad_perm:[2,3,0,1] row_mask:0xf bank_mask:0xf bound_ctrl:1
	s_nop 1
	v_add_f32_dpp v135, v135, v135 row_ror:4 row_mask:0xf bank_mask:0xf bound_ctrl:1
	s_nop 1
	v_add_f32_dpp v135, v135, v135 row_ror:8 row_mask:0xf bank_mask:0xf bound_ctrl:1
	v_mov_b32_e32 v138, v135
	s_nop 1
	v_permlane16_swap_b32_e32 v135, v138
	v_add_f32_e32 v138, v135, v138
	v_mul_f32_e32 v135, v131, v160
	v_mul_f32_e32 v142, v197, v135
	v_mov_b32_e32 v140, v138
	v_mov_b32_dpp v139, v135 quad_perm:[1,0,3,2] row_mask:0xf bank_mask:0xf bound_ctrl:1
	v_mov_b32_dpp v142, v142 quad_perm:[1,0,3,2] row_mask:0xf bank_mask:0xf bound_ctrl:1
	v_fmac_f32_e32 v139, v131, v160
	v_fmac_f32_e32 v142, v197, v135
	v_permlane32_swap_b32_e32 v138, v140
	v_add_f32_dpp v139, v139, v139 quad_perm:[2,3,0,1] row_mask:0xf bank_mask:0xf bound_ctrl:1
	v_add_f32_dpp v135, v142, v142 quad_perm:[2,3,0,1] row_mask:0xf bank_mask:0xf bound_ctrl:1
	s_nop 0
	v_add_f32_dpp v139, v139, v139 row_ror:4 row_mask:0xf bank_mask:0xf bound_ctrl:1
	v_add_f32_dpp v135, v135, v135 row_ror:4 row_mask:0xf bank_mask:0xf bound_ctrl:1
	s_nop 0
	v_add_f32_dpp v139, v139, v139 row_ror:8 row_mask:0xf bank_mask:0xf bound_ctrl:1
	v_add_f32_dpp v135, v135, v135 row_ror:8 row_mask:0xf bank_mask:0xf bound_ctrl:1
	v_mov_b32_e32 v141, v139
	v_mov_b32_e32 v142, v135
	s_nop 0
	v_permlane16_swap_b32_e32 v139, v141
	v_permlane16_swap_b32_e32 v135, v142
	v_add_f32_e32 v139, v139, v141
	v_add_f32_e32 v169, v135, v142
	v_mov_b32_e32 v141, v139
	v_mov_b32_e32 v217, v169
	s_nop 0
	v_permlane32_swap_b32_e32 v139, v141
	v_permlane32_swap_b32_e32 v169, v217
	v_mov_b32_e32 v135, v187
	s_cbranch_scc1 .LBB0_815
	s_add_i32 s2, s23, 0xffffbc7f
	v_mad_u64_u32 v[142:143], s[2:3], s2, v210, v[178:179]
	global_load_dword v144, v[142:143], off
	global_load_dword v135, v[142:143], off offset:1536
	global_load_dword v168, v[142:143], off offset:3072
; __device__ __forceinline__ float bf2f(bf16_t b) { return __uint_as_float(((unsigned)b) << 16); }
; __device__ __forceinline__ float sigmoidf_(float x) { return 1.f / (1.f + __expf(-x)); }
; __device__ __forceinline__ void p2_rwkv_prep(const Params& P, float* lds) {
;     ...
;             for (int tk = tg; tk < tg + 4; ++tk) {
;                 const int tok = tok0 + tk;
;                 if (tok >= NTOK) { const float* p = P.state_shift + (size_t)(tok - NTOK) * RCOLS + tid; qr = p[0]; qk = p[RW]; qv = p[2 * RW]; }
;                 const float cr = nr[tk & 3], ck = nk[tk & 3], cv = nv[tk & 3];
;                 if (tk + 4 < CT) { const bf16_t* p = prw + (size_t)(tok + 4) * RCOLS + tid; nr[tk & 3] = bf2f(p[0]); nk[tk & 3] = bf2f(p[RW]); nv[tk & 3] = bf2f(p[2 * RW]); }
;                 const float r = cr + (qr - cr) * mur, kraw = ck + (qk - ck) * muk, v = cv + (qv - cv) * muv;
;                 qr = cr; qk = ck; qv = cv;
;                 const float aw = w0c + yt[tk * 64 + cc], aa = a0c + yt[(CT + tk) * 64 + cc];
;                 const float w = __expf(-DECAY_SCALE * sigmoidf_(aw)), a = sigmoidf_(aa);
;                 const float kkv = kraw * kkc;
;                 const float n2 = wave_sum_fast(kkv * kkv);
;                 const float kk = kkv * rsqrtf(fmaxf(n2, 1e-12f));
;                 const float kmod = kraw * (1.f + (a - 1.f) * kac);
;                 const float bb = kk * a;
;                 const float br = wave_sum_fast(bb * r);
;                 ekk[tk - tg] = kk; ew[tk - tg] = w; ebb[tk - tg] = bb; ekm[tk - tg] = kmod; ewr[tk - tg] = w * r - kk * br; ev[tk - tg] = v;
;                 ebr[tk - tg] = br; ekr[tk - tg] = wave_sum_fast(kmod * r); erk[tk - tg] = wave_sum_fast(r * kmod * rkc);
.LBB0_815:
	ds_read2st64_b32 v[142:143], v199 offset0:38 offset1:46
	v_lshlrev_b32_e32 v184, 16, v162
	v_lshlrev_b32_e32 v185, 16, v164
	s_waitcnt vmcnt(1)
	v_sub_f32_e32 v135, v135, v185
	v_fma_f32 v135, v195, v135, v185
	s_waitcnt lgkmcnt(0)
	v_add_f32_e32 v143, v194, v143
	v_mul_f32_e32 v143, 0xbfb8aa3b, v143
	v_exp_f32_e32 v145, v143
	v_sub_f32_e32 v143, v144, v184
	v_lshlrev_b32_e32 v216, 16, v163
	v_fma_f32 v143, v196, v143, v184
	v_add_f32_e32 v144, 1.0, v145
	v_div_scale_f32 v145, s[2:3], v144, v144, 1.0
	v_rcp_f32_e32 v146, v145
	v_div_scale_f32 v147, vcc, 1.0, v144, 1.0
	s_cmpk_lt_i32 s21, 0x4000
	v_fma_f32 v150, -v145, v146, 1.0
	v_fmac_f32_e32 v146, v150, v146
	v_mul_f32_e32 v150, v147, v146
	v_fma_f32 v151, -v145, v150, v147
	v_fmac_f32_e32 v150, v151, v146
	v_fma_f32 v145, -v145, v150, v147
	v_mul_f32_e32 v147, v193, v135
	v_mul_f32_e32 v151, v147, v147
	v_div_fmas_f32 v145, v145, v146, v150
	v_div_fixup_f32 v144, v145, v144, 1.0
	v_mov_b32_dpp v151, v151 quad_perm:[1,0,3,2] row_mask:0xf bank_mask:0xf bound_ctrl:1
	v_fmac_f32_e32 v151, v147, v147
	v_add_f32_e32 v145, -1.0, v144
	v_fma_f32 v145, v192, v145, 1.0
	v_add_f32_dpp v151, v151, v151 quad_perm:[2,3,0,1] row_mask:0xf bank_mask:0xf bound_ctrl:1
	v_mul_f32_e32 v164, v135, v145
	v_mov_b32_e32 v162, v216
	v_add_f32_dpp v151, v151, v151 row_ror:4 row_mask:0xf bank_mask:0xf bound_ctrl:1
	v_mov_b32_e32 v221, v184
	s_nop 0
	v_add_f32_dpp v151, v151, v151 row_ror:8 row_mask:0xf bank_mask:0xf bound_ctrl:1
	v_mov_b32_e32 v153, v151
	s_nop 1
	v_permlane16_swap_b32_e32 v151, v153
	v_add_f32_e32 v151, v151, v153
	v_mov_b32_e32 v153, v151
	s_nop 1
	v_permlane32_swap_b32_e32 v151, v153
	v_add_f32_e32 v151, v151, v153
	v_max_f32_e32 v151, 0x2b8cbccc, v151
	v_rsq_f32_e32 v151, v151
	v_mov_b32_e32 v153, v185
	v_mul_f32_e32 v163, v147, v151
	v_mul_f32_e32 v218, v144, v163
	v_mul_f32_e32 v135, v143, v218
	s_nop 1
	v_mov_b32_dpp v135, v135 quad_perm:[1,0,3,2] row_mask:0xf bank_mask:0xf bound_ctrl:1
	v_fmac_f32_e32 v135, v143, v218
	s_nop 1
	v_add_f32_dpp v135, v135, v135 quad_perm:[2,3,0,1] row_mask:0xf bank_mask:0xf bound_ctrl:1
	s_nop 1
	v_add_f32_dpp v135, v135, v135 row_ror:4 row_mask:0xf bank_mask:0xf bound_ctrl:1
	s_nop 1
	v_add_f32_dpp v135, v135, v135 row_ror:8 row_mask:0xf bank_mask:0xf bound_ctrl:1
	v_mov_b32_e32 v144, v135
	s_nop 1
	v_permlane16_swap_b32_e32 v135, v144
	v_add_f32_e32 v144, v135, v144
	v_mul_f32_e32 v135, v143, v164
	v_mul_f32_e32 v150, v197, v135
	v_mov_b32_e32 v146, v144
	v_mov_b32_dpp v145, v135 quad_perm:[1,0,3,2] row_mask:0xf bank_mask:0xf bound_ctrl:1
	v_mov_b32_dpp v150, v150 quad_perm:[1,0,3,2] row_mask:0xf bank_mask:0xf bound_ctrl:1
	v_fmac_f32_e32 v145, v143, v164
	v_fmac_f32_e32 v150, v197, v135
	v_permlane32_swap_b32_e32 v144, v146
	v_add_f32_dpp v145, v145, v145 quad_perm:[2,3,0,1] row_mask:0xf bank_mask:0xf bound_ctrl:1
	v_add_f32_dpp v135, v150, v150 quad_perm:[2,3,0,1] row_mask:0xf bank_mask:0xf bound_ctrl:1
	s_nop 0
	v_add_f32_dpp v145, v145, v145 row_ror:4 row_mask:0xf bank_mask:0xf bound_ctrl:1
	v_add_f32_dpp v135, v135, v135 row_ror:4 row_mask:0xf bank_mask:0xf bound_ctrl:1
	s_nop 0
	v_add_f32_dpp v145, v145, v145 row_ror:8 row_mask:0xf bank_mask:0xf bound_ctrl:1
	v_add_f32_dpp v135, v135, v135 row_ror:8 row_mask:0xf bank_mask:0xf bound_ctrl:1
	v_mov_b32_e32 v147, v145
	v_mov_b32_e32 v150, v135
	s_nop 0
	v_permlane16_swap_b32_e32 v145, v147
	v_permlane16_swap_b32_e32 v135, v150
	v_add_f32_e32 v145, v145, v147
	v_add_f32_e32 v219, v135, v150
	v_mov_b32_e32 v147, v145
	v_mov_b32_e32 v220, v219
	s_nop 0
	v_permlane32_swap_b32_e32 v145, v147
	v_permlane32_swap_b32_e32 v219, v220
	s_cbranch_scc1 .LBB0_817
	s_add_i32 s2, s23, 0xffffbc80
	v_mad_u64_u32 v[150:151], s[2:3], s2, v210, v[178:179]
	global_load_dword v221, v[150:151], off
	global_load_dword v153, v[150:151], off offset:1536
	global_load_dword v162, v[150:151], off offset:3072

; __device__ __forceinline__ float bf2f(bf16_t b) { return __uint_as_float(((unsigned)b) << 16); }
; __device__ __forceinline__ void prep_produce(const Params& P, const bf16_t* __restrict__ prw, int ch, float* buf, int j, float mux) {
;     ...
;     const int tok0 = ch * CT;
;     float pv = 0.f;
;     if (tok0 < NTOK && (tok0 & (SEQ - 1))) pv = bf2f(prw[(size_t)(tok0 - 1) * RCOLS + 1152 + j]);
;     float cur[CT];
; #pragma unroll
;     for (int tk = 0; tk < CT; ++tk) cur[tk] = bf2f(prw[(size_t)(tok0 + tk) * RCOLS + 1152 + j]);
; __device__ __forceinline__ void p2_rwkv_prep(const Params& P, float* lds) {
;     ...
;         if (tid >= RW) { if (ch + NPREP < NCHK) prep_produce(P, prw, ch + NPREP, bufn, tid - RW, mux); }
.LBB0_834:
	s_andn2_saveexec_b64 s[0:1], s[0:1]
	s_cbranch_execz .LBB0_763
	s_cmpk_gt_i32 s30, 0x793
	s_cbranch_scc1 .LBB0_763
	s_add_i32 s16, s30, 0x70
	s_cmpk_gt_i32 s30, 0x78f
	s_cselect_b64 s[2:3], -1, 0
	s_and_b32 s16, s16, 0x1ff
	s_cmp_eq_u32 s16, 0
	s_cselect_b64 s[16:17], -1, 0
	s_or_b64 s[16:17], s[2:3], s[16:17]
	v_mov_b32_e32 v130, 0
	s_and_b64 vcc, exec, s[16:17]
	s_cbranch_vccnz .LBB0_838
	s_add_i32 s16, s23, -8
	v_mad_i64_i32 v[130:131], s[16:17], s16, v208, v[180:181]
	global_load_ushort v1, v[130:131], off offset:2304
	s_waitcnt vmcnt(0)
	v_lshlrev_b32_e32 v130, 16, v1

; #define LAS __attribute__((address_space(3)))
; __device__ __forceinline__ unsigned xb_ld(unsigned* p)              { return __hip_atomic_load(p, __ATOMIC_RELAXED, __HIP_MEMORY_SCOPE_AGENT); }
; __device__ __forceinline__ void sb_decode_wave_loop(const Params& P, float* lds) {
;     unsigned* qd = (unsigned*)(P.ws + WS_BAR) + QW_DEC;
;     const int lane = threadIdx.x & 63;
;     volatile LAS unsigned* scw = (volatile LAS unsigned*)((LAS unsigned char*)lds + SC_CTL_OFF_FWD);
;     unsigned nxt = 0u;
;     if (lane == 0) nxt = atomicAdd(qd, 2u);
;     for (;;) {
;         const int t = __builtin_amdgcn_readfirstlane((int)nxt);
;         if (t >= DEC_NTASK) break;
;         if (lane == 0) nxt = atomicAdd(qd, 2u);
; __device__ __forceinline__ void p3_scan_and_sb(const Params& P, float* lds) {
;     ...
;     if (blockIdx.x < 96) {
;         const int bh = blockIdx.x >> 2, quarter = blockIdx.x & 3, b = bh / RH, h = bh % RH;
;         volatile LAS unsigned* scw = (volatile LAS unsigned*)((LAS unsigned char*)lds + SC_CTL_OFF);
;         if (tid < 5) scw[tid] = 0u;
;         if (tid == 0) { XB_SPIN(xb_ld(ctl + QW_PREP_W) < (unsigned)NPREP, ctl); __builtin_amdgcn_fence(__ATOMIC_ACQUIRE, "agent"); asm volatile("s_waitcnt vmcnt(0)" ::: "memory"); }
;         __syncthreads();
;         scan_prompt_wave(P, (unsigned char*)lds, b, h, quarter);
;         if (wave >= 5 + SC_FREE_WAVES) {
;             constexpr unsigned NCHU = SEQ / SCH;
;             while (scw[1] < NCHU || scw[2] < NCHU || scw[3] < NCHU || scw[4] < NCHU) __builtin_amdgcn_s_sleep(32);
;         }
;     } else {
;         const int grp = wave >> 2, gw = wave & 3;
;         volatile LAS unsigned* gctl = (volatile LAS unsigned*)((LAS unsigned char*)lds + LDS_CTL + 32);
;         if (tid < 8) gctl[tid] = 0u;
;         __syncthreads();
;         sba::Grp4 G; G.ctr = gctl + grp; G.gen = 0u;
;         if (grp == 1) sb_decode_wave_loop(P, lds);
;         {
;             volatile LAS unsigned* qw = gctl + 4 + grp;
;             unsigned* qhead = (unsigned*)(P.ws + WS_BAR) + QW_SB;
;             const bool popper = (gw == 0 && lane == 0);
;             unsigned nxt = 0u;
;             if (popper) nxt = atomicAdd(qhead, 1u);
.LBB0_939:
	s_cmp_lt_i32 s60, 4
	s_cselect_b64 s[0:1], -1, 0
	s_cmp_gt_i32 s61, 3
	s_cselect_b64 s[2:3], -1, 0
	s_and_b64 s[34:35], s[0:1], s[2:3]
	s_andn2_b64 vcc, exec, s[34:35]
	s_cbranch_vccnz .LBB0_1576
	v_writelane_b32 v252, s34, 54
	s_cmpk_lt_u32 s56, 0x60
	v_and_b32_e32 v1, 63, v0
	v_writelane_b32 v252, s35, 55
	v_writelane_b32 v252, s80, 56
	s_cselect_b64 s[52:53], -1, 0
	s_cmpk_gt_u32 s56, 0x5f
	v_writelane_b32 v252, s81, 57
	v_writelane_b32 v252, s56, 53
	v_writelane_b32 v252, s60, 51
	s_mov_b64 s[0:1], -1
	s_waitcnt vmcnt(0)
	v_writelane_b32 v252, s61, 52
	s_barrier
	v_writelane_b32 v252, s57, 50
	s_cbranch_scc0 .LBB0_1203
	v_writelane_b32 v252, s52, 58
	v_cmp_gt_u32_e32 vcc, 8, v0
	s_nop 0
	v_writelane_b32 v252, s53, 59
	s_and_saveexec_b64 s[0:1], vcc
	v_lshl_add_u32 v2, v0, 2, 0
	v_add_u32_e32 v2, 0x26020, v2
	v_mov_b32_e32 v3, 0
	ds_write_b32 v2, v3
	s_or_b64 exec, exec, s[0:1]
	v_lshrrev_b32_e32 v94, 8, v0
	s_waitcnt lgkmcnt(0)
	s_barrier
	v_cmp_eq_u32_e32 vcc, 1, v94
	s_mov_b64 s[0:1], exec
	v_writelane_b32 v252, s0, 60
	s_nop 1
	v_writelane_b32 v252, s1, 61
	s_cmpk_gt_u32 s56, 0x6f
	s_cselect_b64 s[2:3], exec, 0
	s_or_b64 vcc, vcc, s[2:3]
	s_and_b64 s[0:1], s[0:1], vcc
	s_mov_b64 exec, s[0:1]
	s_cbranch_execz .LBB0_1092
	v_readfirstlane_b32 s2, v94
	s_cmp_eq_u32 s2, 0
	s_cselect_b32 s100, 2, 0x7fffffff
	s_add_u32 s0, s78, 0x3900
	s_addc_u32 s1, s79, 0
	v_writelane_b32 v252, s0, 62
	v_mov_b32_e32 v95, 0
	v_cmp_eq_u32_e64 s[4:5], 0, v1
	v_writelane_b32 v252, s1, 63
	s_and_saveexec_b64 s[0:1], s[4:5]
	v_readlane_b32 s22, v252, 48
	v_readlane_b32 s23, v252, 49
	s_cbranch_execz .LBB0_948
	s_mov_b64 s[6:7], exec
	v_mbcnt_lo_u32_b32 v2, s6, 0
	v_mbcnt_hi_u32_b32 v2, s7, v2
	v_cmp_eq_u32_e32 vcc, 0, v2
	s_and_saveexec_b64 s[2:3], vcc
	s_cbranch_execz .LBB0_947
	s_bcnt1_i32_b64 s6, s[6:7]
	s_lshl_b32 s6, s6, 1
	v_mov_b32_e32 v4, s6
	v_readlane_b32 s6, v252, 62
	v_mov_b32_e32 v3, 0
	v_readlane_b32 s7, v252, 63
	s_nop 4
	global_atomic_add v3, v3, v4, s[6:7] sc0

; #define LAS __attribute__((address_space(3)))
; __device__ __forceinline__ unsigned xb_ld(unsigned* p)              { return __hip_atomic_load(p, __ATOMIC_RELAXED, __HIP_MEMORY_SCOPE_AGENT); }
; #define XB_SPIN(cond, bar) do { unsigned _sp = 0; while (cond) { __builtin_amdgcn_s_sleep(1); \
;     if ((++_sp & 255u) == 0u) { if (xb_ld(&(bar)[XB_TMO])) break; if (_sp > XB_SPIN_CAP) { atomicAdd(&(bar)[XB_TMO], 1u); break; } } } } while (0)
; __device__ __forceinline__ void p3_scan_and_sb(const Params& P, float* lds) {
;     ...
;     if (blockIdx.x < 96) {
;         const int bh = blockIdx.x >> 2, quarter = blockIdx.x & 3, b = bh / RH, h = bh % RH;
;         volatile LAS unsigned* scw = (volatile LAS unsigned*)((LAS unsigned char*)lds + SC_CTL_OFF);
;         if (tid < 5) scw[tid] = 0u;
;         if (tid == 0) { XB_SPIN(xb_ld(ctl + QW_PREP_W) < (unsigned)NPREP, ctl); __builtin_amdgcn_fence(__ATOMIC_ACQUIRE, "agent"); asm volatile("s_waitcnt vmcnt(0)" ::: "memory"); }
;         __syncthreads();
.LBB0_1203:
	s_and_b64 vcc, exec, s[0:1]
	s_cbranch_vccz .LBB0_1261
	v_cmp_gt_u32_e32 vcc, 5, v0
	s_and_saveexec_b64 s[0:1], vcc
	v_lshl_add_u32 v2, v0, 2, 0
	v_add_u32_e32 v2, 0x23000, v2
	v_mov_b32_e32 v3, 0
	ds_write_b32 v2, v3
	s_or_b64 exec, exec, s[0:1]
	s_and_saveexec_b64 s[0:1], s[80:81]
	s_cbranch_execz .LBB0_1221
	v_mov_b32_e32 v2, 0x3000
	global_load_dword v2, v2, s[78:79] offset:3328 sc1
	s_movk_i32 s10, 0x6f
	s_add_u32 s2, s78, 0x3d00
	s_addc_u32 s3, s79, 0
	s_waitcnt vmcnt(0)
	v_cmp_lt_u32_e32 vcc, s10, v2
	s_cbranch_vccnz .LBB0_1220
	s_mov_b32 s11, 1
	v_mov_b32_e32 v2, 0
	s_branch .LBB0_1210

; __device__ __forceinline__ unsigned xb_ld(unsigned* p)              { return __hip_atomic_load(p, __ATOMIC_RELAXED, __HIP_MEMORY_SCOPE_AGENT); }
; #define XB_SPIN(cond, bar) do { unsigned _sp = 0; while (cond) { __builtin_amdgcn_s_sleep(1); \
;     if ((++_sp & 255u) == 0u) { if (xb_ld(&(bar)[XB_TMO])) break; if (_sp > XB_SPIN_CAP) { atomicAdd(&(bar)[XB_TMO], 1u); break; } } } } while (0)
; __device__ __forceinline__ void p3_scan_and_sb(const Params& P, float* lds) {
;     ...
;     sb_decode_wave_loop(P, lds);
;     if (lane == 0) XB_SPIN(xb_ld(ctl + QW_PREP_W) < (unsigned)NPREP, ctl);
;     __builtin_amdgcn_fence(__ATOMIC_ACQUIRE, "agent");
.LBB0_1555:
	s_and_saveexec_b64 s[0:1], s[4:5]
	v_readlane_b32 s58, v252, 48
	v_readlane_b32 s59, v252, 49
	s_load_dwordx8 s[68:75], s[58:59], 0xc0
	v_readlane_b32 s80, v252, 56
	v_readlane_b32 s60, v252, 51
	v_readlane_b32 s34, v252, 54
	v_readlane_b32 s81, v252, 57
	v_readlane_b32 s56, v252, 53
	v_readlane_b32 s61, v252, 52
	v_readlane_b32 s57, v252, 50
	v_readlane_b32 s35, v252, 55
	s_cbranch_execz .LBB0_1568
	v_mov_b32_e32 v1, 0x3000
	global_load_dword v1, v1, s[78:79] offset:3328 sc1
	s_movk_i32 s10, 0x6f
	s_add_u32 s2, s78, 0x3d00
	s_addc_u32 s3, s79, 0
	s_waitcnt vmcnt(0)
	v_cmp_lt_u32_e32 vcc, s10, v1
	s_cbranch_vccnz .LBB0_1568
	s_mov_b32 s11, 1
	v_mov_b32_e32 v1, 0
	s_branch .LBB0_1559
